# diff attention: K/V LDS tile double-buffered (one barrier per 64-key step) and static s_setprio 1 for waves 0-3 inside the item
# speedup vs baseline: 1.0792x; 1.0020x over previous
;   __device__ __forceinline__ u16* P() const { return (u16*)(ws + O_P); }
; DI int ltid() { int t = threadIdx.x; asm volatile("" : "+v"(t)); return t; }
; DI float bf2f(u16 h) { return __uint_as_float(((u32)h) << 16); }
; #define DLOAD(kt) { DLOAD1(0, kt) DLOAD1(1, kt) }
; DI void diff_item(const Params& p, int l, int qt, int bh, char* smem) {
;   const int b = bh >> 2, h = bh & 3;
;   const int tid = ltid(), ln = tid & 63, w = tid >> 6, hh = ln >> 5, c31 = ln & 31;
;   const int st = w & 3, c = w >> 2;
;   const size_t tokbase = (size_t)b * T;
;   const int qb = qt * 128 + 32 * st + c31;
;   u16* proj = p.P();
;   bf16x8 qf[4];
;   {
;     const u16* qrow = proj + (tokbase + qb) * PC + AQ + h * 128 + c * 64 + 8 * hh;
; #pragma unroll
;     for (int s = 0; s < 4; ++s) {
;       const bf16x8 q = *(const bf16x8*)(qrow + 16 * s);
;       typedef __bf16 bf16v8q_ __attribute__((ext_vector_type(8)));
;       bf16v8q_ v;
; #pragma unroll
;       for (int j = 0; j < 8; ++j) v[j] = (__bf16)(bf2f((u16)q[j]) * (0.125f * 1.44269504089f));
;       qf[s] = __builtin_bit_cast(bf16x8, v);
;     }
;   }
;   f32x16 O[4];
;   float mrun, lrun;
;   f32x16 Lacc;
;   bf16x8 onesf;
;   {
;     const short o1 = (c31 == 0) ? (short)0x3F80 : (short)0;
;     onesf = bf16x8{o1, o1, o1, o1, o1, o1, o1, o1};
;   }
;   const bf16x8 onesK = (hh == 0) ? bf16x8{(short)0x3F80, 0, 0, 0, 0, 0, 0, 0} : bf16x8{0, 0, 0, 0, 0, 0, 0, 0};
;   bf16x8 mfrag = bf16x8{0, 0, 0, 0, 0, 0, 0, 0};
;   const float sc = 0.125f * 1.44269504089f;
;   char* Ks = smem;
;   char* Vs = smem + 17408;
;   uint4 rk0, rk1, rv0, rv1;
;   const int srow = tid >> 4, sch = tid & 15;
;     ...
;   const int nkt = 2 * qt + 2;
; #pragma unroll 1
;   for (int rep = 0; rep < DUP_DIFF; ++rep) {
; #pragma unroll
;   for (int i = 0; i < 4; ++i)
; #pragma unroll
;     for (int j = 0; j < 16; ++j) O[i][j] = 0.f;
;   mrun = 0.f; lrun = 0.f;
;   mfrag = bf16x8{0, 0, 0, 0, 0, 0, 0, 0};
; #pragma unroll
;   for (int j = 0; j < 16; ++j) Lacc[j] = 0.f;
;   DLOAD(0);
.LBB0_575:
	s_and_b64 vcc, exec, s[0:1]
	s_cbranch_vccz .LBB0_593
	s_waitcnt vmcnt(0)
	v_cmp_gt_u32_e32 vcc, 0x100, v171
	s_cbranch_vccz .Ldf_noprio
	s_setprio 1
.Ldf_noprio:
	v_mov_b32_e32 v157, v171
	s_sub_i32 s2, 0x7f, s61
	v_lshrrev_b32_e32 v0, 1, v157
	v_and_b32_e32 v167, 0x60, v0
	v_and_b32_e32 v163, 31, v157
	s_lshl_b32 s0, s60, 12
	v_lshl_or_b32 v37, s2, 7, v167
	s_and_b32 s54, s0, 0x4000
	v_or_b32_e32 v156, v37, v163
	v_or_b32_e32 v0, s54, v156
	v_mul_u32_u24_e32 v0, 0xfd0, v0
	s_lshl_b32 s0, s60, 7
	v_ashrrev_i32_e32 v166, 8, v157
	v_lshlrev_b32_e32 v0, 1, v0
	s_and_b32 s4, s0, 0x180
	v_lshl_add_u64 v[2:3], s[78:79], 0, v[0:1]
	s_lshl_b32 s0, s4, 1
	s_mov_b32 s1, s55
	v_lshlrev_b32_e32 v4, 6, v166
	v_bfe_u32 v36, v157, 5, 1
	v_lshl_add_u64 v[2:3], v[2:3], 0, s[0:1]
	v_ashrrev_i32_e32 v5, 31, v4
	v_lshl_add_u64 v[2:3], v[4:5], 1, v[2:3]
	v_lshlrev_b32_e32 v158, 4, v36
	v_mov_b32_e32 v159, v1
	v_lshl_add_u64 v[14:15], v[2:3], 0, v[158:159]
	global_load_dwordx4 v[2:5], v[14:15], off
	global_load_dwordx4 v[6:9], v[14:15], off offset:32
	global_load_dwordx4 v[10:13], v[14:15], off offset:64
	s_nop 0
	global_load_dwordx4 v[14:17], v[14:15], off offset:96
	v_ashrrev_i32_e32 v38, 4, v157
	v_mov_b64_e32 v[18:19], s[78:79]
	v_add_u32_e32 v20, s54, v38
	v_lshlrev_b32_e32 v39, 4, v157
	v_mad_i64_i32 v[18:19], s[6:7], v20, s91, v[18:19]
	v_lshl_add_u64 v[18:19], v[18:19], 0, s[0:1]
	v_and_b32_e32 v160, 0xf0, v39
	v_mov_b32_e32 v161, v1
	s_mov_b64 s[0:1], 0x3f400
	s_lshl_b32 s6, s2, 1
	s_movk_i32 s2, 0xffd0
	v_cmp_eq_u32_e32 vcc, 0, v163
	v_and_b32_e32 v0, 63, v157
	v_or_b32_e32 v173, 31, v37
	v_lshlrev_b32_e32 v159, 2, v36
	v_mov_b32_e32 v152, 0
	s_mov_b32 s5, 0
	v_lshl_or_b32 v175, v166, 7, v158
	v_mul_u32_u24_e32 v176, 0x110, v163
	s_mov_b32 s8, 0
	v_mov_b32_e32 v153, v152
	v_mov_b32_e32 v154, v152
	v_mov_b32_e32 v155, v152
	s_mov_b32 s9, 0x41000000
	s_waitcnt vmcnt(3)
	v_and_b32_e32 v21, 0xffff0000, v2
	v_lshlrev_b32_e32 v20, 16, v2
	v_and_b32_e32 v23, 0xffff0000, v3
	v_lshlrev_b32_e32 v22, 16, v3
	v_and_b32_e32 v3, 0xffff0000, v4
	v_lshlrev_b32_e32 v2, 16, v4
	v_and_b32_e32 v25, 0xffff0000, v5
	v_lshlrev_b32_e32 v24, 16, v5
	s_waitcnt vmcnt(2)
	v_and_b32_e32 v5, 0xffff0000, v6
	v_lshlrev_b32_e32 v4, 16, v6
	v_pk_mul_f32 v[2:3], v[2:3], s[58:59] op_sel_hi:[1,0]
	v_pk_mul_f32 v[4:5], v[4:5], s[58:59] op_sel_hi:[1,0]
	v_cvt_pk_bf16_f32 v134, v2, v3
	v_lshl_add_u64 v[2:3], v[18:19], 0, v[160:161]
	v_cvt_pk_bf16_f32 v128, v4, v5
	v_lshl_add_u64 v[4:5], v[2:3], 0, s[0:1]
	global_load_dwordx4 v[140:143], v[2:3], off offset:1024
	global_load_dwordx4 v[136:139], v[2:3], off offset:2048
	global_load_dwordx4 v[144:147], v[4:5], off offset:1024
	global_load_dwordx4 v[148:151], v[4:5], off offset:2048
	s_movk_i32 s0, 0x140
	v_and_b32_e32 v27, 0xffff0000, v7
	v_lshlrev_b32_e32 v26, 16, v7
	v_and_b32_e32 v7, 0xffff0000, v8
	v_lshlrev_b32_e32 v6, 16, v8
	v_pk_mul_f32 v[20:21], v[20:21], s[58:59] op_sel_hi:[1,0]
	v_mul_lo_u32 v162, v38, s0
	v_pk_mul_f32 v[6:7], v[6:7], s[58:59] op_sel_hi:[1,0]
	v_cvt_pk_bf16_f32 v132, v20, v21
	v_mad_u64_u32 v[20:21], s[2:3], v38, s2, v[162:163]
	v_cvt_pk_bf16_f32 v130, v6, v7
	v_and_b32_e32 v5, 16, v157
	v_lshlrev_b32_e32 v7, 2, v157
	s_lshl_b32 s2, s61, 1
	v_and_b32_e32 v29, 0xffff0000, v9
	v_lshlrev_b32_e32 v28, 16, v9
	s_waitcnt vmcnt(5)
	v_and_b32_e32 v9, 0xffff0000, v10
	v_lshlrev_b32_e32 v8, 16, v10
	v_and_b32_e32 v31, 0xffff0000, v11
	v_lshlrev_b32_e32 v30, 16, v11
	v_and_b32_e32 v11, 0xffff0000, v12
	v_lshlrev_b32_e32 v10, 16, v12
	v_and_b32_e32 v33, 0xffff0000, v13
	v_lshlrev_b32_e32 v32, 16, v13
	s_waitcnt vmcnt(4)
	v_and_b32_e32 v13, 0xffff0000, v14
	v_lshlrev_b32_e32 v12, 16, v14
	v_and_b32_e32 v35, 0xffff0000, v15
	v_lshlrev_b32_e32 v34, 16, v15
	v_and_b32_e32 v15, 0xffff0000, v16
	v_lshlrev_b32_e32 v14, 16, v16
	v_and_or_b32 v5, v7, 12, v5
	s_sub_i32 s7, 0xff, s2
	s_bfe_u32 s2, s60, 0x10002
	s_and_b32 s3, s60, 3
	v_pk_mul_f32 v[2:3], v[14:15], s[58:59] op_sel_hi:[1,0]
	v_lshrrev_b32_e32 v6, 3, v157
	v_lshlrev_b32_e32 v168, 1, v5
	v_bfe_u32 v5, v157, 2, 2
	s_mul_i32 s2, s2, 0x7e80000
	s_lshl_b32 s3, s3, 8
	v_cvt_pk_bf16_f32 v122, v2, v3
	v_and_b32_e32 v3, 0xffff0000, v17
	v_lshlrev_b32_e32 v2, 16, v17
	v_cndmask_b32_e32 v4, 0, v206, vcc
	v_and_or_b32 v5, v6, 4, v5
	s_or_b32 s2, s2, s3
	v_pk_mul_f32 v[2:3], v[2:3], s[58:59] op_sel_hi:[1,0]
	v_perm_b32 v116, v4, v4, s66
	v_mul_u32_u24_e32 v169, 0x140, v5
	v_mov_b32_e32 v4, s2
	v_mov_b32_e32 v5, v1
	v_cvt_pk_bf16_f32 v123, v2, v3
	v_mul_lo_u32 v2, v38, s68
	v_mad_i64_i32 v[4:5], s[2:3], v38, s91, v[4:5]
	v_pk_mul_f32 v[22:23], v[22:23], s[58:59] op_sel_hi:[1,0]
	v_mul_lo_u32 v3, v38, 48
	v_add_u32_e32 v177, 0x2200, v2
	s_movk_i32 s0, 0x600
	v_readlane_b32 s2, v253, 62
	v_pk_mul_f32 v[24:25], v[24:25], s[58:59] op_sel_hi:[1,0]
	v_pk_mul_f32 v[26:27], v[26:27], s[58:59] op_sel_hi:[1,0]
	v_pk_mul_f32 v[28:29], v[28:29], s[58:59] op_sel_hi:[1,0]
	v_pk_mul_f32 v[8:9], v[8:9], s[58:59] op_sel_hi:[1,0]
	v_pk_mul_f32 v[30:31], v[30:31], s[58:59] op_sel_hi:[1,0]
	v_pk_mul_f32 v[10:11], v[10:11], s[58:59] op_sel_hi:[1,0]
	v_pk_mul_f32 v[32:33], v[32:33], s[58:59] op_sel_hi:[1,0]
	v_pk_mul_f32 v[12:13], v[12:13], s[58:59] op_sel_hi:[1,0]
	v_pk_mul_f32 v[34:35], v[34:35], s[58:59] op_sel_hi:[1,0]
	v_cvt_pk_bf16_f32 v133, v22, v23
	v_add3_u32 v22, v3, v177, s0
	v_lshl_add_u64 v[4:5], v[4:5], 0, v[160:161]
	v_readlane_b32 s3, v253, 63
	v_mov_b32_e32 v18, v1
	v_mov_b32_e32 v19, v1
	v_cvt_pk_bf16_f32 v135, v24, v25
	v_cvt_pk_bf16_f32 v129, v26, v27
	v_cvt_pk_bf16_f32 v131, v28, v29
	v_cvt_pk_bf16_f32 v124, v8, v9
	v_cvt_pk_bf16_f32 v125, v30, v31
	v_cvt_pk_bf16_f32 v126, v10, v11
; DI f32x16 mfma32(bf16x8 a, bf16x8 b, f32x16 c) { return __builtin_amdgcn_mfma_f32_32x32x16_bf16(a, b, c, 0, 0, 0); }
; #define DLOAD(kt) { DLOAD1(0, kt) DLOAD1(1, kt) }
; DI void diff_item(const Params& p, int l, int qt, int bh, char* smem) {
;     ...
;   float mrun, lrun;
;   f32x16 Lacc;
;   bf16x8 onesf;
;   {
;     const short o1 = (c31 == 0) ? (short)0x3F80 : (short)0;
;     onesf = bf16x8{o1, o1, o1, o1, o1, o1, o1, o1};
;   }
;   const bf16x8 onesK = (hh == 0) ? bf16x8{(short)0x3F80, 0, 0, 0, 0, 0, 0, 0} : bf16x8{0, 0, 0, 0, 0, 0, 0, 0};
;   bf16x8 mfrag = bf16x8{0, 0, 0, 0, 0, 0, 0, 0};
;   const float sc = 0.125f * 1.44269504089f;
;   char* Ks = smem;
;   char* Vs = smem + 17408;
;   uint4 rk0, rk1, rv0, rv1;
;   const int srow = tid >> 4, sch = tid & 15;
;     ...
;   const int nkt = 2 * qt + 2;
; #pragma unroll 1
;   for (int rep = 0; rep < DUP_DIFF; ++rep) {
; #pragma unroll
;   for (int i = 0; i < 4; ++i)
; #pragma unroll
;     for (int j = 0; j < 16; ++j) O[i][j] = 0.f;
;   mrun = 0.f; lrun = 0.f;
;   mfrag = bf16x8{0, 0, 0, 0, 0, 0, 0, 0};
; #pragma unroll
;   for (int j = 0; j < 16; ++j) Lacc[j] = 0.f;
;   DLOAD(0);
;     ...
; #pragma unroll
;     for (int k2 = 0; k2 < 2; ++k2)
; #pragma unroll
;       for (int s2 = 0; s2 < 2; ++s2) {
;         const bf16x8 pp = pack8(sa[k2], s2);
;         bf16x8 vf[4];
;         trfrag4<320>(Vs, 32 * k2 + 16 * s2, ln, vf);
; #pragma unroll
;         for (int mt = 0; mt < 4; ++mt) O[mt] = mfma32(vf[mt], pp, O[mt]);
;         Lacc = mfma32(onesf, pp, Lacc);
;       }
	v_cvt_pk_bf16_f32 v127, v32, v33
	v_cvt_pk_bf16_f32 v120, v12, v13
	v_cvt_pk_bf16_f32 v121, v34, v35
	v_cmp_gt_u32_e64 s[0:1], 32, v0
	v_lshl_add_u64 v[164:165], s[2:3], 0, v[4:5]
	v_mov_b32_e32 v4, v1
	v_mov_b32_e32 v5, v1
	v_mov_b32_e32 v6, v1
	v_mov_b32_e32 v7, v1
	v_mov_b32_e32 v8, v1
	v_mov_b32_e32 v9, v1
	v_mov_b32_e32 v10, v1
	v_mov_b32_e32 v11, v1
	v_mov_b32_e32 v12, v1
	v_mov_b32_e32 v13, v1
	v_mov_b32_e32 v14, v1
	v_mov_b32_e32 v15, v1
	v_mov_b32_e32 v16, v1
	v_mov_b32_e32 v17, v1
	v_add_u32_e32 v179, v20, v160
	v_add_u32_e32 v178, v22, v160
	v_mov_b64_e32 v[34:35], v[18:19]
	v_mov_b64_e32 v[50:51], v[18:19]
	v_mov_b64_e32 v[66:67], v[18:19]
	v_mov_b64_e32 v[82:83], v[18:19]
	v_cndmask_b32_e64 v0, 0, v206, s[0:1]
	v_mov_b32_e32 v2, v1
	v_mov_b32_e32 v3, v1
	v_mov_b32_e32 v117, v116
	v_mov_b32_e32 v118, v116
	v_mov_b32_e32 v119, v116
	v_mov_b32_e32 v161, 0
	v_mov_b64_e32 v[32:33], v[16:17]
	v_mov_b64_e32 v[30:31], v[14:15]
	v_mov_b64_e32 v[28:29], v[12:13]
	v_mov_b64_e32 v[26:27], v[10:11]
	v_mov_b64_e32 v[24:25], v[8:9]
	v_mov_b64_e32 v[22:23], v[6:7]
	v_mov_b64_e32 v[20:21], v[4:5]
	v_mov_b64_e32 v[48:49], v[16:17]
	v_mov_b64_e32 v[46:47], v[14:15]
	v_mov_b64_e32 v[44:45], v[12:13]
	v_mov_b64_e32 v[42:43], v[10:11]
	v_mov_b64_e32 v[40:41], v[8:9]
	v_mov_b64_e32 v[38:39], v[6:7]
	v_mov_b64_e32 v[36:37], v[4:5]
	v_mov_b64_e32 v[64:65], v[16:17]
	v_mov_b64_e32 v[62:63], v[14:15]
	v_mov_b64_e32 v[60:61], v[12:13]
	v_mov_b64_e32 v[58:59], v[10:11]
	v_mov_b64_e32 v[56:57], v[8:9]
	v_mov_b64_e32 v[54:55], v[6:7]
	v_mov_b64_e32 v[52:53], v[4:5]
	v_mov_b64_e32 v[80:81], v[16:17]
	v_mov_b64_e32 v[78:79], v[14:15]
	v_mov_b64_e32 v[76:77], v[12:13]
	v_mov_b64_e32 v[74:75], v[10:11]
	v_mov_b64_e32 v[72:73], v[8:9]
	v_mov_b64_e32 v[70:71], v[6:7]
	v_mov_b64_e32 v[68:69], v[4:5]
	s_mov_b32 s98, 0x9400
	s_branch .LBB0_579
.LBB0_577:
	v_add3_u32 v182, v168, v169, s98
	s_waitcnt lgkmcnt(1)
	ds_read_b64_tr_b16 v[226:227], v182 offset:22528
	ds_read_b64_tr_b16 v[228:229], v182 offset:25088
	ds_read_b64_tr_b16 v[230:231], v182 offset:22592
	ds_read_b64_tr_b16 v[232:233], v182 offset:25152
	ds_read_b64_tr_b16 v[234:235], v182 offset:22656
	ds_read_b64_tr_b16 v[236:237], v182 offset:25216
	ds_read_b64_tr_b16 v[238:239], v182 offset:22720
	ds_read_b64_tr_b16 v[240:241], v182 offset:25280
	v_exp_f32_e32 v84, v84
	v_exp_f32_e32 v85, v85
	v_exp_f32_e32 v86, v86
	v_exp_f32_e32 v87, v87
	v_exp_f32_e32 v88, v88
	v_exp_f32_e32 v89, v89
	v_exp_f32_e32 v90, v90
	v_exp_f32_e32 v91, v91
	v_exp_f32_e32 v92, v92
	v_exp_f32_e32 v93, v93
	v_cvt_pk_bf16_f32 v84, v84, v85
	v_cvt_pk_bf16_f32 v85, v86, v87
	v_cvt_pk_bf16_f32 v86, v88, v89
	v_cvt_pk_bf16_f32 v87, v90, v91
	s_nop 0
	s_waitcnt lgkmcnt(8)
	v_mfma_f32_32x32x16_bf16 v[52:67], v[210:213], v[84:87], v[52:67]
	v_exp_f32_e32 v94, v94
	v_exp_f32_e32 v95, v95
	v_mfma_f32_32x32x16_bf16 v[36:51], v[214:217], v[84:87], v[36:51]
	v_exp_f32_e32 v96, v96
	v_exp_f32_e32 v97, v97
	v_mfma_f32_32x32x16_bf16 v[20:35], v[218:221], v[84:87], v[20:35]
	v_exp_f32_e32 v98, v98
	v_exp_f32_e32 v99, v99
	v_mfma_f32_32x32x16_bf16 v[4:19], v[222:225], v[84:87], v[4:19]
	v_exp_f32_e32 v100, v100
	v_exp_f32_e32 v101, v101
	ds_read_b64_tr_b16 v[210:211], v182 offset:27648
	ds_read_b64_tr_b16 v[212:213], v182 offset:30208
	ds_read_b64_tr_b16 v[214:215], v182 offset:27712
	ds_read_b64_tr_b16 v[216:217], v182 offset:30272
	ds_read_b64_tr_b16 v[218:219], v182 offset:27776
	ds_read_b64_tr_b16 v[220:221], v182 offset:30336
	ds_read_b64_tr_b16 v[222:223], v182 offset:27840
	ds_read_b64_tr_b16 v[224:225], v182 offset:30400
	v_mfma_f32_32x32x16_bf16 v[68:83], v[116:119], v[84:87], v[68:83]
	v_cvt_pk_bf16_f32 v92, v92, v93
	v_cvt_pk_bf16_f32 v93, v94, v95
	v_cvt_pk_bf16_f32 v94, v96, v97
	v_cvt_pk_bf16_f32 v95, v98, v99
	s_nop 0
	s_waitcnt lgkmcnt(8)
	v_mfma_f32_32x32x16_bf16 v[52:67], v[226:229], v[92:95], v[52:67]
	v_exp_f32_e32 v102, v102
	v_exp_f32_e32 v103, v103
	v_mfma_f32_32x32x16_bf16 v[36:51], v[230:233], v[92:95], v[36:51]
	v_exp_f32_e32 v104, v104
	v_exp_f32_e32 v105, v105
	v_mfma_f32_32x32x16_bf16 v[20:35], v[234:237], v[92:95], v[20:35]
	v_exp_f32_e32 v106, v106
	v_exp_f32_e32 v107, v107
	v_mfma_f32_32x32x16_bf16 v[4:19], v[238:241], v[92:95], v[4:19]
	v_exp_f32_e32 v108, v108
	v_exp_f32_e32 v109, v109
	ds_read_b64_tr_b16 v[226:227], v182 offset:32768
	ds_read_b64_tr_b16 v[228:229], v182 offset:35328
	ds_read_b64_tr_b16 v[230:231], v182 offset:32832
	ds_read_b64_tr_b16 v[232:233], v182 offset:35392
	ds_read_b64_tr_b16 v[234:235], v182 offset:32896
	ds_read_b64_tr_b16 v[236:237], v182 offset:35456
	ds_read_b64_tr_b16 v[238:239], v182 offset:32960
	ds_read_b64_tr_b16 v[240:241], v182 offset:35520
	v_mfma_f32_32x32x16_bf16 v[68:83], v[116:119], v[92:95], v[68:83]
	v_cvt_pk_bf16_f32 v100, v100, v101
	v_cvt_pk_bf16_f32 v101, v102, v103
	v_cvt_pk_bf16_f32 v102, v104, v105
	v_cvt_pk_bf16_f32 v103, v106, v107
	s_nop 0
	s_waitcnt lgkmcnt(8)
	v_mfma_f32_32x32x16_bf16 v[52:67], v[210:213], v[100:103], v[52:67]
	v_exp_f32_e32 v110, v110
	v_exp_f32_e32 v111, v111
	v_mfma_f32_32x32x16_bf16 v[36:51], v[214:217], v[100:103], v[36:51]
	v_exp_f32_e32 v112, v112
	v_exp_f32_e32 v113, v113
	v_mfma_f32_32x32x16_bf16 v[20:35], v[218:221], v[100:103], v[20:35]
	v_exp_f32_e32 v114, v114
	v_exp_f32_e32 v115, v115
	v_mfma_f32_32x32x16_bf16 v[4:19], v[222:225], v[100:103], v[4:19]
	v_mfma_f32_32x32x16_bf16 v[68:83], v[116:119], v[100:103], v[68:83]
	v_cvt_pk_bf16_f32 v108, v108, v109
	v_cvt_pk_bf16_f32 v109, v110, v111
	v_cvt_pk_bf16_f32 v110, v112, v113
	v_cvt_pk_bf16_f32 v111, v114, v115
	s_nop 0
	s_waitcnt lgkmcnt(0)
	v_mfma_f32_32x32x16_bf16 v[52:67], v[226:229], v[108:111], v[52:67]
	v_mfma_f32_32x32x16_bf16 v[36:51], v[230:233], v[108:111], v[36:51]
	v_mfma_f32_32x32x16_bf16 v[20:35], v[234:237], v[108:111], v[20:35]
	v_mfma_f32_32x32x16_bf16 v[4:19], v[238:241], v[108:111], v[4:19]
	v_mfma_f32_32x32x16_bf16 v[68:83], v[116:119], v[108:111], v[68:83]

; DI f32x16 mfma32(bf16x8 a, bf16x8 b, f32x16 c) { return __builtin_amdgcn_mfma_f32_32x32x16_bf16(a, b, c, 0, 0, 0); }
; DI int crow(int i, int hh) { return (i & 3) + 8 * (i >> 2) + 4 * hh; }
; #define DLOAD(kt) { DLOAD1(0, kt) DLOAD1(1, kt) }
; DI void diff_item(const Params& p, int l, int qt, int bh, char* smem) {
;     ...
;   for (int kt = 0; kt < nkt; ++kt) {
;     __syncthreads();
;     DSTORE1(0) DSTORE1(1)
;     __syncthreads();
;     if (kt + 1 < nkt) { DLOAD(kt + 1); }
;     if (kt * 64 > qt * 128 + 32 * st + 31) continue;
;     f32x16 sa[2];
; #pragma unroll
;     for (int k2 = 0; k2 < 2; ++k2) {
; #pragma unroll
;       for (int j = 0; j < 16; ++j) sa[k2][j] = 0.f;
; #pragma unroll
;       for (int s = 0; s < 4; ++s)
;         sa[k2] = mfma32(*(const bf16x8*)(Ks + (32 * k2 + c31) * 272 + (c * 64 + 16 * s + 8 * hh) * 2), qf[s], sa[k2]);
;       sa[k2] = mfma32(onesK, mfrag, sa[k2]);
;     }
;     if (kt >= 2 * qt) {
; #pragma unroll
;       for (int k2 = 0; k2 < 2; ++k2)
; #pragma unroll
;         for (int j = 0; j < 16; ++j)
;           if (kt * 64 + 32 * k2 + crow(j, hh) > qb) sa[k2][j] = -INFINITY;
;     }
.LBB0_579:
	s_xor_b32 s98, s98, 0x9400
	v_add_co_u32_e32 v84, vcc, 0x3f000, v164
	v_add3_u32 v180, v162, v160, s98
	v_add3_u32 v181, v177, v160, s98
	v_addc_co_u32_e32 v85, vcc, 0, v165, vcc
	v_add_u32_e32 v242, s98, v179
	v_add_u32_e32 v243, s98, v178
	s_waitcnt vmcnt(3)
	ds_write_b128 v242, v[140:143]
	s_waitcnt vmcnt(2)
	ds_write_b128 v180, v[136:139] offset:17408
	s_waitcnt vmcnt(1)
	ds_write_b128 v181, v[144:147]
	s_waitcnt vmcnt(0)
	ds_write_b128 v243, v[148:151] offset:17408
	s_waitcnt lgkmcnt(0)
	s_barrier
	global_load_dwordx4 v[140:143], v[164:165], off
	global_load_dwordx4 v[136:139], v[164:165], off offset:1024
	global_load_dwordx4 v[144:147], v[84:85], off offset:1024
	global_load_dwordx4 v[148:151], v[84:85], off offset:2048
	v_cmp_le_u32_e32 vcc, s5, v173
	s_and_saveexec_b64 s[2:3], vcc
	s_cbranch_execz .LBB0_578
	v_add3_u32 v186, v176, v175, s98
	ds_read_b128 v[210:213], v186
	ds_read_b128 v[214:217], v186 offset:32
	ds_read_b128 v[218:221], v186 offset:64
	ds_read_b128 v[222:225], v186 offset:96
	ds_read_b128 v[226:229], v186 offset:8704
	ds_read_b128 v[230:233], v186 offset:8736
	ds_read_b128 v[234:237], v186 offset:8768
	ds_read_b128 v[238:241], v186 offset:8800
	s_cmp_lt_u32 s8, s6
	s_waitcnt lgkmcnt(7)
	v_mfma_f32_32x32x16_bf16 v[84:99], v[210:213], v[132:135], 0
	s_waitcnt lgkmcnt(6)
	v_mfma_f32_32x32x16_bf16 v[84:99], v[214:217], v[128:131], v[84:99]
	s_waitcnt lgkmcnt(5)
	v_mfma_f32_32x32x16_bf16 v[84:99], v[218:221], v[124:127], v[84:99]
	s_waitcnt lgkmcnt(4)
	v_mfma_f32_32x32x16_bf16 v[84:99], v[222:225], v[120:123], v[84:99]
	s_waitcnt lgkmcnt(3)
	v_mfma_f32_32x32x16_bf16 v[100:115], v[226:229], v[132:135], 0
	s_waitcnt lgkmcnt(2)
	v_mfma_f32_32x32x16_bf16 v[100:115], v[230:233], v[128:131], v[100:115]
	s_waitcnt lgkmcnt(1)
	v_mfma_f32_32x32x16_bf16 v[100:115], v[234:237], v[124:127], v[100:115]
	s_waitcnt lgkmcnt(0)
	v_mfma_f32_32x32x16_bf16 v[100:115], v[238:241], v[120:123], v[100:115]
	v_mfma_f32_32x32x16_bf16 v[84:99], v[0:3], v[152:155], v[84:99]
	v_mfma_f32_32x32x16_bf16 v[100:115], v[0:3], v[152:155], v[100:115]
	v_add3_u32 v182, v168, v169, s98
	ds_read_b64_tr_b16 v[210:211], v182 offset:17408
	ds_read_b64_tr_b16 v[212:213], v182 offset:19968
	ds_read_b64_tr_b16 v[214:215], v182 offset:17472
	ds_read_b64_tr_b16 v[216:217], v182 offset:20032
	ds_read_b64_tr_b16 v[218:219], v182 offset:17536
	ds_read_b64_tr_b16 v[220:221], v182 offset:20096
	ds_read_b64_tr_b16 v[222:223], v182 offset:17600
	ds_read_b64_tr_b16 v[224:225], v182 offset:20160
	s_cbranch_scc1 .LBB0_582
	v_add_u32_e32 v182, s5, v159
	v_cmp_gt_u32_e32 vcc, v182, v156
	s_nop 1
	v_cndmask_b32_e32 v183, v84, v205, vcc
	v_cmp_lt_u32_e32 vcc, v182, v156
	s_nop 1
	v_cndmask_b32_e32 v84, v183, v84, vcc
	v_add_u32_e32 v183, 2, v182
	v_cndmask_b32_e32 v85, v205, v85, vcc
	v_cmp_le_u32_e32 vcc, v183, v156
	v_add_u32_e32 v183, 3, v182
	s_nop 0
	v_cndmask_b32_e32 v86, v205, v86, vcc
	v_cmp_le_u32_e32 vcc, v183, v156
	v_add_u32_e32 v183, 8, v182
	s_nop 0
	v_cndmask_b32_e32 v87, v205, v87, vcc
	v_cmp_le_u32_e32 vcc, v183, v156
	v_add_u32_e32 v183, 9, v182
	s_nop 0
	v_cndmask_b32_e32 v88, v205, v88, vcc
	v_cmp_le_u32_e32 vcc, v183, v156
	v_add_u32_e32 v183, 10, v182
	s_nop 0
	v_cndmask_b32_e32 v89, v205, v89, vcc
	v_cmp_le_u32_e32 vcc, v183, v156
	v_add_u32_e32 v183, 11, v182
	s_nop 0
	v_cndmask_b32_e32 v90, v205, v90, vcc
	v_cmp_le_u32_e32 vcc, v183, v156
	v_add_u32_e32 v183, 16, v182
	s_nop 0
	v_cndmask_b32_e32 v91, v205, v91, vcc
	v_cmp_le_u32_e32 vcc, v183, v156
	v_add_u32_e32 v183, 17, v182
	s_nop 0
	v_cndmask_b32_e32 v92, v205, v92, vcc
	v_cmp_le_u32_e32 vcc, v183, v156
	v_add_u32_e32 v183, 18, v182
	s_nop 0
	v_cndmask_b32_e32 v93, v205, v93, vcc
	v_cmp_le_u32_e32 vcc, v183, v156
	v_add_u32_e32 v183, 19, v182
	s_nop 0
	v_cndmask_b32_e32 v94, v205, v94, vcc
	v_cmp_le_u32_e32 vcc, v183, v156
	v_add_u32_e32 v183, 24, v182
	s_nop 0
	v_cndmask_b32_e32 v95, v205, v95, vcc
	v_cmp_le_u32_e32 vcc, v183, v156
	v_add_u32_e32 v183, 25, v182
	s_nop 0
	v_cndmask_b32_e32 v96, v205, v96, vcc
	v_cmp_le_u32_e32 vcc, v183, v156
	v_add_u32_e32 v183, 26, v182
	s_nop 0
	v_cndmask_b32_e32 v97, v205, v97, vcc
	v_cmp_le_u32_e32 vcc, v183, v156
	v_add_u32_e32 v183, 27, v182
	s_nop 0
	v_cndmask_b32_e32 v98, v205, v98, vcc
	v_cmp_le_u32_e32 vcc, v183, v156
	v_add_u32_e32 v183, 32, v182
	s_nop 0
	v_cndmask_b32_e32 v99, v205, v99, vcc
	v_cmp_le_u32_e32 vcc, v183, v156
	v_add_u32_e32 v183, 33, v182
	s_nop 0
	v_cndmask_b32_e32 v100, v205, v100, vcc
	v_cmp_le_u32_e32 vcc, v183, v156
	v_add_u32_e32 v183, 34, v182
	s_nop 0
	v_cndmask_b32_e32 v101, v205, v101, vcc
	v_cmp_le_u32_e32 vcc, v183, v156
	v_add_u32_e32 v183, 35, v182
	s_nop 0
	v_cndmask_b32_e32 v102, v205, v102, vcc
	v_cmp_le_u32_e32 vcc, v183, v156
	v_add_u32_e32 v183, 40, v182
	s_nop 0
	v_cndmask_b32_e32 v103, v205, v103, vcc
	v_cmp_le_u32_e32 vcc, v183, v156
	v_add_u32_e32 v183, 41, v182
	s_nop 0
	v_cndmask_b32_e32 v104, v205, v104, vcc
	v_cmp_le_u32_e32 vcc, v183, v156
	v_add_u32_e32 v183, 42, v182
	s_nop 0
	v_cndmask_b32_e32 v105, v205, v105, vcc
	v_cmp_le_u32_e32 vcc, v183, v156
	v_add_u32_e32 v183, 43, v182
	s_nop 0
	v_cndmask_b32_e32 v106, v205, v106, vcc
	v_cmp_le_u32_e32 vcc, v183, v156
	v_add_u32_e32 v183, 48, v182
	s_nop 0
	v_cndmask_b32_e32 v107, v205, v107, vcc
	v_cmp_le_u32_e32 vcc, v183, v156
	v_add_u32_e32 v183, 49, v182
	s_nop 0
	v_cndmask_b32_e32 v108, v205, v108, vcc
	v_cmp_le_u32_e32 vcc, v183, v156
	v_add_u32_e32 v183, 50, v182
	s_nop 0
	v_cndmask_b32_e32 v109, v205, v109, vcc
	v_cmp_le_u32_e32 vcc, v183, v156
	v_add_u32_e32 v183, 51, v182
	s_nop 0
	v_cndmask_b32_e32 v110, v205, v110, vcc
	v_cmp_le_u32_e32 vcc, v183, v156
	v_add_u32_e32 v183, 56, v182
	s_nop 0
	v_cndmask_b32_e32 v111, v205, v111, vcc
	v_cmp_le_u32_e32 vcc, v183, v156
	v_add_u32_e32 v183, 57, v182
	s_nop 0
	v_cndmask_b32_e32 v112, v205, v112, vcc
	v_cmp_le_u32_e32 vcc, v183, v156
	v_add_u32_e32 v183, 58, v182
	v_add_u32_e32 v182, 59, v182
	v_cndmask_b32_e32 v113, v205, v113, vcc
	v_cmp_le_u32_e32 vcc, v183, v156
	s_nop 1
	v_cndmask_b32_e32 v114, v205, v114, vcc
	v_cmp_le_u32_e32 vcc, v182, v156
	s_nop 1
	v_cndmask_b32_e32 v115, v205, v115, vcc

; DI f32x16 mfma32(bf16x8 a, bf16x8 b, f32x16 c) { return __builtin_amdgcn_mfma_f32_32x32x16_bf16(a, b, c, 0, 0, 0); }
; DI int crow(int i, int hh) { return (i & 3) + 8 * (i >> 2) + 4 * hh; }
; #define DLOAD(kt) { DLOAD1(0, kt) DLOAD1(1, kt) }
; DI void diff_item(const Params& p, int l, int qt, int bh, char* smem) {
;     ...
;   for (int kt = 0; kt < nkt; ++kt) {
;     __syncthreads();
;     DSTORE1(0) DSTORE1(1)
;     __syncthreads();
;     if (kt + 1 < nkt) { DLOAD(kt + 1); }
;     if (kt * 64 > qt * 128 + 32 * st + 31) continue;
;     f32x16 sa[2];
; #pragma unroll
;     for (int k2 = 0; k2 < 2; ++k2) {
; #pragma unroll
;       for (int j = 0; j < 16; ++j) sa[k2][j] = 0.f;
; #pragma unroll
;       for (int s = 0; s < 4; ++s)
;         sa[k2] = mfma32(*(const bf16x8*)(Ks + (32 * k2 + c31) * 272 + (c * 64 + 16 * s + 8 * hh) * 2), qf[s], sa[k2]);
;       sa[k2] = mfma32(onesK, mfrag, sa[k2]);
;     }
;     if (kt >= 2 * qt) {
; #pragma unroll
;       for (int k2 = 0; k2 < 2; ++k2)
; #pragma unroll
;         for (int j = 0; j < 16; ++j)
;           if (kt * 64 + 32 * k2 + crow(j, hh) > qb) sa[k2][j] = -INFINITY;
;     }
;     float tmax = sa[0][0];
; #pragma unroll
;     for (int k2 = 0; k2 < 2; ++k2)
; #pragma unroll
;       for (int j = 0; j < 16; ++j) tmax = fmaxf(tmax, sa[k2][j]);
;     tmax = xhalf_max(tmax);
;     if (__any(tmax > 8.f)) {
.LBB0_584:
	v_cmp_le_u32_e32 vcc, s5, v173
	s_xor_b32 s98, s98, 0x9400
	v_add3_u32 v180, v162, v160, s98
	v_add3_u32 v181, v177, v160, s98
	v_add_u32_e32 v242, s98, v179
	v_add_u32_e32 v243, s98, v178
	s_barrier
	s_waitcnt vmcnt(3)
	ds_write_b128 v242, v[140:143]
	s_waitcnt vmcnt(2)
	ds_write_b128 v180, v[136:139] offset:17408
	s_waitcnt vmcnt(1)
	ds_write_b128 v181, v[144:147]
	s_waitcnt vmcnt(0)
	ds_write_b128 v243, v[148:151] offset:17408
	s_waitcnt lgkmcnt(0)
	s_barrier
	s_and_saveexec_b64 s[0:1], vcc
	s_cbranch_execz .LBB0_588
	v_add3_u32 v92, v176, v175, s98
	ds_read_b128 v[84:87], v92
	ds_read_b128 v[88:91], v92 offset:32
	v_or_b32_e32 v148, s5, v159
	v_cmp_le_u32_e32 vcc, v148, v156
	v_or_b32_e32 v149, 10, v148
	s_waitcnt lgkmcnt(1)
	v_mfma_f32_32x32x16_bf16 v[100:115], v[84:87], v[132:135], 0
	v_or_b32_e32 v150, 11, v148
	v_or_b32_e32 v151, 16, v148
	s_waitcnt lgkmcnt(0)
	v_mfma_f32_32x32x16_bf16 v[100:115], v[88:91], v[128:131], v[100:115]
	ds_read_b128 v[84:87], v92 offset:64
	ds_read_b128 v[88:91], v92 offset:96
	s_waitcnt lgkmcnt(1)
	v_mfma_f32_32x32x16_bf16 v[100:115], v[84:87], v[124:127], v[100:115]
	ds_read_b128 v[84:87], v92 offset:8704
	ds_read_b128 v[136:139], v92 offset:8736
	ds_read_b128 v[140:143], v92 offset:8768
	ds_read_b128 v[144:147], v92 offset:8800
	s_waitcnt lgkmcnt(4)
	v_mfma_f32_32x32x16_bf16 v[100:115], v[88:91], v[120:123], v[100:115]
	s_waitcnt lgkmcnt(3)
	v_mfma_f32_32x32x16_bf16 v[84:99], v[84:87], v[132:135], 0
	v_or_b32_e32 v132, 2, v148
	v_or_b32_e32 v133, 3, v148
	v_or_b32_e32 v134, 8, v148
	v_or_b32_e32 v135, 9, v148
	s_waitcnt lgkmcnt(2)
	v_mfma_f32_32x32x16_bf16 v[84:99], v[136:139], v[128:131], v[84:99]
	v_mfma_f32_32x32x16_bf16 v[100:115], v[0:3], v[152:155], v[100:115]
	s_waitcnt lgkmcnt(1)
	v_mfma_f32_32x32x16_bf16 v[84:99], v[140:143], v[124:127], v[84:99]
	s_nop 9
	v_cndmask_b32_e32 v100, v205, v100, vcc
	v_cmp_lt_u32_e32 vcc, v148, v156
	s_nop 1
	v_cndmask_b32_e32 v101, v205, v101, vcc
	v_cmp_le_u32_e32 vcc, v132, v156
	s_waitcnt lgkmcnt(0)
	v_mfma_f32_32x32x16_bf16 v[84:99], v[144:147], v[120:123], v[84:99]
	v_cndmask_b32_e32 v132, v205, v102, vcc
	v_cmp_le_u32_e32 vcc, v133, v156
	s_nop 1
	v_cndmask_b32_e32 v133, v205, v103, vcc
	v_cmp_le_u32_e32 vcc, v134, v156
	v_mfma_f32_32x32x16_bf16 v[84:99], v[0:3], v[152:155], v[84:99]
	s_nop 0
	v_cndmask_b32_e32 v102, v205, v104, vcc
	v_cmp_le_u32_e32 vcc, v135, v156
	v_or_b32_e32 v0, 33, v148
	s_nop 0
	v_cndmask_b32_e32 v103, v205, v105, vcc
	v_cmp_le_u32_e32 vcc, v149, v156
	s_nop 1
	v_cndmask_b32_e32 v104, v205, v106, vcc
	v_cmp_le_u32_e32 vcc, v150, v156
	s_nop 1
	v_cndmask_b32_e32 v105, v205, v107, vcc
	v_cmp_le_u32_e32 vcc, v151, v156
	v_or_b32_e32 v107, 17, v148
	s_nop 0
	v_cndmask_b32_e32 v106, v205, v108, vcc
	v_cmp_le_u32_e32 vcc, v107, v156
	v_or_b32_e32 v108, 18, v148
	s_nop 0
	v_cndmask_b32_e32 v107, v205, v109, vcc
	v_cmp_le_u32_e32 vcc, v108, v156
	v_or_b32_e32 v109, 19, v148
	s_nop 0
	v_cndmask_b32_e32 v108, v205, v110, vcc
	v_cmp_le_u32_e32 vcc, v109, v156
	v_or_b32_e32 v110, 24, v148
	s_nop 0
	v_cndmask_b32_e32 v109, v205, v111, vcc
	v_cmp_le_u32_e32 vcc, v110, v156
	v_or_b32_e32 v111, 25, v148
	s_nop 0
	v_cndmask_b32_e32 v110, v205, v112, vcc
	v_cmp_le_u32_e32 vcc, v111, v156
	v_or_b32_e32 v112, 26, v148
	s_nop 0
	v_cndmask_b32_e32 v111, v205, v113, vcc
	v_cmp_le_u32_e32 vcc, v112, v156
	v_or_b32_e32 v113, 27, v148
	s_nop 0
	v_cndmask_b32_e32 v112, v205, v114, vcc
	v_cmp_le_u32_e32 vcc, v113, v156
	v_or_b32_e32 v114, 32, v148
	s_nop 0
	v_cndmask_b32_e32 v113, v205, v115, vcc
	v_cmp_le_u32_e32 vcc, v114, v156
	s_nop 1
	v_cndmask_b32_e32 v2, v205, v84, vcc
	v_cmp_le_u32_e32 vcc, v0, v156
	v_or_b32_e32 v0, 34, v148
	s_nop 0
	v_cndmask_b32_e32 v3, v205, v85, vcc
	v_cmp_le_u32_e32 vcc, v0, v156
	v_or_b32_e32 v0, 35, v148
	s_nop 0
	v_cndmask_b32_e32 v84, v205, v86, vcc
	v_cmp_le_u32_e32 vcc, v0, v156
	v_or_b32_e32 v0, 40, v148
	s_nop 0
	v_cndmask_b32_e32 v85, v205, v87, vcc
	v_cmp_le_u32_e32 vcc, v0, v156
	v_or_b32_e32 v0, 41, v148
	s_nop 0
	v_cndmask_b32_e32 v86, v205, v88, vcc
	v_cmp_le_u32_e32 vcc, v0, v156
	v_or_b32_e32 v0, 42, v148
	s_nop 0
	v_cndmask_b32_e32 v87, v205, v89, vcc
	v_cmp_le_u32_e32 vcc, v0, v156
	v_or_b32_e32 v0, 43, v148
	s_nop 0
	v_cndmask_b32_e32 v88, v205, v90, vcc
	v_cmp_le_u32_e32 vcc, v0, v156
	v_or_b32_e32 v0, 48, v148
	s_nop 0
	v_cndmask_b32_e32 v89, v205, v91, vcc
	v_cmp_le_u32_e32 vcc, v0, v156
	v_or_b32_e32 v0, 49, v148
	s_nop 0
	v_cndmask_b32_e32 v90, v205, v92, vcc
	v_cmp_le_u32_e32 vcc, v0, v156
	v_or_b32_e32 v0, 50, v148
	s_nop 0
	v_cndmask_b32_e32 v91, v205, v93, vcc
	v_cmp_le_u32_e32 vcc, v0, v156
	v_or_b32_e32 v0, 51, v148
	s_nop 0
	v_cndmask_b32_e32 v92, v205, v94, vcc
	v_cmp_le_u32_e32 vcc, v0, v156
	v_or_b32_e32 v0, 56, v148
	s_nop 0
	v_cndmask_b32_e32 v93, v205, v95, vcc
	v_cmp_le_u32_e32 vcc, v0, v156
	v_or_b32_e32 v0, 57, v148
	s_nop 0
	v_cndmask_b32_e32 v94, v205, v96, vcc
	v_cmp_le_u32_e32 vcc, v0, v156
	v_or_b32_e32 v0, 58, v148
	s_nop 0
	v_cndmask_b32_e32 v95, v205, v97, vcc
	v_cmp_le_u32_e32 vcc, v0, v156
	v_or_b32_e32 v0, 59, v148
	s_nop 0
	v_cndmask_b32_e32 v96, v205, v98, vcc
	v_cmp_le_u32_e32 vcc, v0, v156
	v_max_f32_e32 v0, v101, v101
	v_max_f32_e32 v98, v100, v100
	v_max_f32_e32 v0, v98, v0
	v_max3_f32 v0, v0, v132, v133
	v_max3_f32 v0, v0, v102, v103
	v_max3_f32 v0, v0, v104, v105
	v_max3_f32 v0, v0, v106, v107
	v_max3_f32 v0, v0, v108, v109
	v_max3_f32 v0, v0, v110, v111
	v_max3_f32 v0, v0, v112, v113
	v_max3_f32 v0, v0, v2, v3
	v_max3_f32 v0, v0, v84, v85
	v_max3_f32 v0, v0, v86, v87
	v_max3_f32 v0, v0, v88, v89
	v_max3_f32 v0, v0, v90, v91
	v_max3_f32 v0, v0, v92, v93
	v_cndmask_b32_e32 v97, v205, v99, vcc
	v_max3_f32 v0, v0, v94, v95
	v_max3_f32 v0, v0, v96, v97
	v_mov_b32_e32 v98, v0
	s_nop 1
	v_permlane32_swap_b32_e32 v0, v98
	v_max_f32_e32 v98, v98, v98
	v_max_f32_e32 v0, v0, v0
	v_max_f32_e32 v0, v0, v98
	v_cmp_lt_f32_e32 vcc, s9, v0
	s_cbranch_vccz .LBB0_587
; DI float bf2f(u16 h) { return __uint_as_float(((u32)h) << 16); }
; DI f32x16 mfma32(bf16x8 a, bf16x8 b, f32x16 c) { return __builtin_amdgcn_mfma_f32_32x32x16_bf16(a, b, c, 0, 0, 0); }
; DI void diff_item(const Params& p, int l, int qt, int bh, char* smem) {
;     ...
;     if (__any(tmax > 8.f)) {
;       const float mnew = bf2f(f2bf(mrun + fmaxf(tmax, 0.f)));
;       const float delta = mnew - mrun;
;       const float alpha = __builtin_amdgcn_exp2f(-delta);
;       mrun = mnew;
;       {
;         const short mb = (hh == 0) ? (short)f2bf(-mnew) : (short)0;
;         mfrag = bf16x8{mb, 0, 0, 0, 0, 0, 0, 0};
;       }
; #pragma unroll
;       for (int k2 = 0; k2 < 2; ++k2)
; #pragma unroll
;         for (int j = 0; j < 16; ++j) sa[k2][j] -= delta;
; #pragma unroll
;       for (int j = 0; j < 16; ++j) Lacc[j] *= alpha;
; #pragma unroll
;       for (int i = 0; i < 4; ++i)
; #pragma unroll
;         for (int j = 0; j < 16; ++j) O[i][j] *= alpha;
;     }
; #pragma unroll
;     for (int k2 = 0; k2 < 2; ++k2)
; #pragma unroll
;       for (int j = 0; j < 16; ++j) sa[k2][j] = __builtin_amdgcn_exp2f(sa[k2][j]);
; #pragma unroll
;     for (int k2 = 0; k2 < 2; ++k2)
; #pragma unroll
;       for (int s2 = 0; s2 < 2; ++s2) {
;         const bf16x8 pp = pack8(sa[k2], s2);
;         bf16x8 vf[4];
;         trfrag4<320>(Vs, 32 * k2 + 16 * s2, ln, vf);
; #pragma unroll
;         for (int mt = 0; mt < 4; ++mt) O[mt] = mfma32(vf[mt], pp, O[mt]);
;         Lacc = mfma32(onesf, pp, Lacc);
;       }
	v_max_f32_e32 v0, v0, v0
	v_max_f32_e32 v0, 0, v0
	v_add_f32_e32 v0, v161, v0
	v_cvt_pk_bf16_f32 v0, v0, s0
	v_lshlrev_b32_e32 v0, 16, v0
	v_sub_f32_e32 v0, v0, v161
	v_exp_f32_e64 v98, -v0
	v_pk_add_f32 v[100:101], v[100:101], v[0:1] op_sel_hi:[1,0] neg_lo:[0,1] neg_hi:[0,1]
	v_pk_add_f32 v[132:133], v[132:133], v[0:1] op_sel_hi:[1,0] neg_lo:[0,1] neg_hi:[0,1]
	v_pk_add_f32 v[102:103], v[102:103], v[0:1] op_sel_hi:[1,0] neg_lo:[0,1] neg_hi:[0,1]
	v_pk_add_f32 v[104:105], v[104:105], v[0:1] op_sel_hi:[1,0] neg_lo:[0,1] neg_hi:[0,1]
	v_pk_add_f32 v[106:107], v[106:107], v[0:1] op_sel_hi:[1,0] neg_lo:[0,1] neg_hi:[0,1]
	v_pk_add_f32 v[108:109], v[108:109], v[0:1] op_sel_hi:[1,0] neg_lo:[0,1] neg_hi:[0,1]
	v_pk_add_f32 v[110:111], v[110:111], v[0:1] op_sel_hi:[1,0] neg_lo:[0,1] neg_hi:[0,1]
	v_pk_add_f32 v[112:113], v[112:113], v[0:1] op_sel_hi:[1,0] neg_lo:[0,1] neg_hi:[0,1]
	v_pk_add_f32 v[2:3], v[2:3], v[0:1] op_sel_hi:[1,0] neg_lo:[0,1] neg_hi:[0,1]
	v_pk_add_f32 v[84:85], v[84:85], v[0:1] op_sel_hi:[1,0] neg_lo:[0,1] neg_hi:[0,1]
	v_pk_add_f32 v[86:87], v[86:87], v[0:1] op_sel_hi:[1,0] neg_lo:[0,1] neg_hi:[0,1]
	v_pk_add_f32 v[88:89], v[88:89], v[0:1] op_sel_hi:[1,0] neg_lo:[0,1] neg_hi:[0,1]
	v_pk_add_f32 v[90:91], v[90:91], v[0:1] op_sel_hi:[1,0] neg_lo:[0,1] neg_hi:[0,1]
	v_pk_add_f32 v[92:93], v[92:93], v[0:1] op_sel_hi:[1,0] neg_lo:[0,1] neg_hi:[0,1]
	v_pk_add_f32 v[94:95], v[94:95], v[0:1] op_sel_hi:[1,0] neg_lo:[0,1] neg_hi:[0,1]
	v_pk_add_f32 v[96:97], v[96:97], v[0:1] op_sel_hi:[1,0] neg_lo:[0,1] neg_hi:[0,1]
	v_pk_mul_f32 v[66:67], v[66:67], v[98:99] op_sel_hi:[1,0]
	v_pk_mul_f32 v[64:65], v[64:65], v[98:99] op_sel_hi:[1,0]
	v_pk_mul_f32 v[62:63], v[62:63], v[98:99] op_sel_hi:[1,0]
	v_pk_mul_f32 v[60:61], v[60:61], v[98:99] op_sel_hi:[1,0]
	v_pk_mul_f32 v[58:59], v[58:59], v[98:99] op_sel_hi:[1,0]
	v_pk_mul_f32 v[56:57], v[56:57], v[98:99] op_sel_hi:[1,0]
	v_pk_mul_f32 v[54:55], v[54:55], v[98:99] op_sel_hi:[1,0]
	v_pk_mul_f32 v[52:53], v[52:53], v[98:99] op_sel_hi:[1,0]
	v_pk_mul_f32 v[50:51], v[50:51], v[98:99] op_sel_hi:[1,0]
	v_pk_mul_f32 v[48:49], v[48:49], v[98:99] op_sel_hi:[1,0]
	v_pk_mul_f32 v[46:47], v[46:47], v[98:99] op_sel_hi:[1,0]
	v_pk_mul_f32 v[44:45], v[44:45], v[98:99] op_sel_hi:[1,0]
	v_pk_mul_f32 v[42:43], v[42:43], v[98:99] op_sel_hi:[1,0]
	v_pk_mul_f32 v[40:41], v[40:41], v[98:99] op_sel_hi:[1,0]
	v_pk_mul_f32 v[38:39], v[38:39], v[98:99] op_sel_hi:[1,0]
	v_pk_mul_f32 v[36:37], v[36:37], v[98:99] op_sel_hi:[1,0]
	v_pk_mul_f32 v[34:35], v[34:35], v[98:99] op_sel_hi:[1,0]
	v_pk_mul_f32 v[32:33], v[32:33], v[98:99] op_sel_hi:[1,0]
	v_pk_mul_f32 v[30:31], v[30:31], v[98:99] op_sel_hi:[1,0]
	v_pk_mul_f32 v[28:29], v[28:29], v[98:99] op_sel_hi:[1,0]
	v_pk_mul_f32 v[26:27], v[26:27], v[98:99] op_sel_hi:[1,0]
	v_pk_mul_f32 v[24:25], v[24:25], v[98:99] op_sel_hi:[1,0]
	v_pk_mul_f32 v[22:23], v[22:23], v[98:99] op_sel_hi:[1,0]
	v_pk_mul_f32 v[20:21], v[20:21], v[98:99] op_sel_hi:[1,0]
	v_pk_mul_f32 v[18:19], v[18:19], v[98:99] op_sel_hi:[1,0]
	v_pk_mul_f32 v[16:17], v[16:17], v[98:99] op_sel_hi:[1,0]
	v_pk_mul_f32 v[14:15], v[14:15], v[98:99] op_sel_hi:[1,0]
	v_pk_mul_f32 v[12:13], v[12:13], v[98:99] op_sel_hi:[1,0]
	v_pk_mul_f32 v[10:11], v[10:11], v[98:99] op_sel_hi:[1,0]
	v_pk_mul_f32 v[8:9], v[8:9], v[98:99] op_sel_hi:[1,0]
	v_pk_mul_f32 v[6:7], v[6:7], v[98:99] op_sel_hi:[1,0]
	v_pk_mul_f32 v[4:5], v[4:5], v[98:99] op_sel_hi:[1,0]
	v_pk_mul_f32 v[82:83], v[82:83], v[98:99] op_sel_hi:[1,0]
	v_pk_mul_f32 v[80:81], v[80:81], v[98:99] op_sel_hi:[1,0]
	v_pk_mul_f32 v[78:79], v[78:79], v[98:99] op_sel_hi:[1,0]
	v_pk_mul_f32 v[76:77], v[76:77], v[98:99] op_sel_hi:[1,0]
	v_pk_mul_f32 v[74:75], v[74:75], v[98:99] op_sel_hi:[1,0]
	v_pk_mul_f32 v[72:73], v[72:73], v[98:99] op_sel_hi:[1,0]
	v_pk_mul_f32 v[70:71], v[70:71], v[98:99] op_sel_hi:[1,0]
	v_pk_mul_f32 v[68:69], v[68:69], v[98:99] op_sel_hi:[1,0]
.LBB0_587:
	v_exp_f32_e32 v0, v100
	v_exp_f32_e32 v98, v101
	v_exp_f32_e32 v99, v132
	v_exp_f32_e32 v100, v133
	v_exp_f32_e32 v101, v102
	v_exp_f32_e32 v102, v103
	v_exp_f32_e32 v103, v104
	v_exp_f32_e32 v104, v105
	v_exp_f32_e32 v105, v106
	v_exp_f32_e32 v106, v107
	v_exp_f32_e32 v107, v108
	v_exp_f32_e32 v108, v109
	v_exp_f32_e32 v109, v110
	v_exp_f32_e32 v110, v111
	v_exp_f32_e32 v111, v112
	v_exp_f32_e32 v112, v113
	v_exp_f32_e32 v113, v84
	v_cvt_pk_bf16_f32 v84, v0, v98
	v_add3_u32 v0, v168, v169, s98
	v_exp_f32_e32 v114, v85
	v_exp_f32_e32 v115, v86
	v_exp_f32_e32 v120, v87
	v_exp_f32_e32 v121, v88
	v_exp_f32_e32 v122, v89
	v_exp_f32_e32 v123, v90
	v_exp_f32_e32 v124, v91
	v_exp_f32_e32 v125, v92
	v_exp_f32_e32 v126, v93
	v_exp_f32_e32 v127, v94
	v_exp_f32_e32 v128, v95
	v_exp_f32_e32 v129, v96
	v_exp_f32_e32 v130, v97
	v_cvt_pk_bf16_f32 v87, v103, v104
	v_cvt_pk_bf16_f32 v86, v101, v102
	v_cvt_pk_bf16_f32 v85, v99, v100
	ds_read_b64_tr_b16 v[88:89], v0 offset:17408
	ds_read_b64_tr_b16 v[90:91], v0 offset:19968
	ds_read_b64_tr_b16 v[92:93], v0 offset:17472
	ds_read_b64_tr_b16 v[94:95], v0 offset:20032
	ds_read_b64_tr_b16 v[96:97], v0 offset:17536
	ds_read_b64_tr_b16 v[98:99], v0 offset:20096
	ds_read_b64_tr_b16 v[100:101], v0 offset:17600
	ds_read_b64_tr_b16 v[102:103], v0 offset:20160
	s_waitcnt lgkmcnt(6)
	v_mfma_f32_32x32x16_bf16 v[52:67], v[88:91], v[84:87], v[52:67]
	v_exp_f32_e32 v2, v2
	v_exp_f32_e32 v3, v3
	s_waitcnt lgkmcnt(4)
	v_mfma_f32_32x32x16_bf16 v[36:51], v[92:95], v[84:87], v[36:51]
	s_waitcnt lgkmcnt(2)
	v_mfma_f32_32x32x16_bf16 v[20:35], v[96:99], v[84:87], v[20:35]
	s_waitcnt lgkmcnt(0)
; DI f32x16 mfma32(bf16x8 a, bf16x8 b, f32x16 c) { return __builtin_amdgcn_mfma_f32_32x32x16_bf16(a, b, c, 0, 0, 0); }
; DI void diff_item(const Params& p, int l, int qt, int bh, char* smem) {
;     ...
; #pragma unroll
;     for (int k2 = 0; k2 < 2; ++k2)
; #pragma unroll
;       for (int s2 = 0; s2 < 2; ++s2) {
;         const bf16x8 pp = pack8(sa[k2], s2);
;         bf16x8 vf[4];
;         trfrag4<320>(Vs, 32 * k2 + 16 * s2, ln, vf);
; #pragma unroll
;         for (int mt = 0; mt < 4; ++mt) O[mt] = mfma32(vf[mt], pp, O[mt]);
;         Lacc = mfma32(onesf, pp, Lacc);
;       }
;   }
;   }
;     ...
;   __syncthreads();
;   lrun = Lacc[0];
;   const float ltot = xhalf_sum(lrun);
;   const float inv = 1.f / ltot;
;   float* xch = (float*)smem + st * 32 * 132;
;   if (c == 1) {
; #pragma unroll
;     for (int mt = 0; mt < 4; ++mt)
; #pragma unroll
;       for (int i4 = 0; i4 < 4; ++i4)
;         *(float4*)(xch + c31 * 132 + 32 * mt + 8 * i4 + 4 * hh) =
;             float4{O[mt][4 * i4] * inv, O[mt][4 * i4 + 1] * inv, O[mt][4 * i4 + 2] * inv, O[mt][4 * i4 + 3] * inv};
;   }
	v_mfma_f32_32x32x16_bf16 v[4:19], v[100:103], v[84:87], v[4:19]
	ds_read_b64_tr_b16 v[88:89], v0 offset:22528
	ds_read_b64_tr_b16 v[90:91], v0 offset:25088
	ds_read_b64_tr_b16 v[92:93], v0 offset:22592
	ds_read_b64_tr_b16 v[94:95], v0 offset:25152
	ds_read_b64_tr_b16 v[96:97], v0 offset:22656
	ds_read_b64_tr_b16 v[98:99], v0 offset:25216
	ds_read_b64_tr_b16 v[100:101], v0 offset:22720
	ds_read_b64_tr_b16 v[102:103], v0 offset:25280
	v_mfma_f32_32x32x16_bf16 v[68:83], v[116:119], v[84:87], v[68:83]
	v_cvt_pk_bf16_f32 v87, v111, v112
	v_cvt_pk_bf16_f32 v86, v109, v110
	v_cvt_pk_bf16_f32 v85, v107, v108
	v_cvt_pk_bf16_f32 v84, v105, v106
	s_waitcnt lgkmcnt(6)
	s_nop 0
	v_mfma_f32_32x32x16_bf16 v[52:67], v[88:91], v[84:87], v[52:67]
	s_waitcnt lgkmcnt(4)
	v_mfma_f32_32x32x16_bf16 v[36:51], v[92:95], v[84:87], v[36:51]
	s_waitcnt lgkmcnt(2)
	v_mfma_f32_32x32x16_bf16 v[20:35], v[96:99], v[84:87], v[20:35]
	s_waitcnt lgkmcnt(0)
	v_mfma_f32_32x32x16_bf16 v[4:19], v[100:103], v[84:87], v[4:19]
	ds_read_b64_tr_b16 v[88:89], v0 offset:27648
	ds_read_b64_tr_b16 v[90:91], v0 offset:30208
	ds_read_b64_tr_b16 v[92:93], v0 offset:27712
	ds_read_b64_tr_b16 v[94:95], v0 offset:30272
	ds_read_b64_tr_b16 v[96:97], v0 offset:27776
	ds_read_b64_tr_b16 v[98:99], v0 offset:30336
	ds_read_b64_tr_b16 v[100:101], v0 offset:27840
	ds_read_b64_tr_b16 v[102:103], v0 offset:30400
	v_mfma_f32_32x32x16_bf16 v[68:83], v[116:119], v[84:87], v[68:83]
	v_cvt_pk_bf16_f32 v87, v121, v122
	v_cvt_pk_bf16_f32 v86, v115, v120
	v_cvt_pk_bf16_f32 v85, v113, v114
	v_cvt_pk_bf16_f32 v84, v2, v3
	s_waitcnt lgkmcnt(6)
	s_nop 0
	v_mfma_f32_32x32x16_bf16 v[52:67], v[88:91], v[84:87], v[52:67]
	s_waitcnt lgkmcnt(4)
	v_mfma_f32_32x32x16_bf16 v[36:51], v[92:95], v[84:87], v[36:51]
	s_waitcnt lgkmcnt(2)
	v_mfma_f32_32x32x16_bf16 v[20:35], v[96:99], v[84:87], v[20:35]
	s_waitcnt lgkmcnt(0)
	v_mfma_f32_32x32x16_bf16 v[4:19], v[100:103], v[84:87], v[4:19]
	ds_read_b64_tr_b16 v[88:89], v0 offset:32768
	ds_read_b64_tr_b16 v[90:91], v0 offset:35328
	ds_read_b64_tr_b16 v[92:93], v0 offset:32832
	ds_read_b64_tr_b16 v[94:95], v0 offset:35392
	ds_read_b64_tr_b16 v[96:97], v0 offset:32896
	ds_read_b64_tr_b16 v[98:99], v0 offset:35456
	ds_read_b64_tr_b16 v[100:101], v0 offset:32960
	ds_read_b64_tr_b16 v[102:103], v0 offset:35520
	v_mfma_f32_32x32x16_bf16 v[68:83], v[116:119], v[84:87], v[68:83]
	v_cvt_pk_bf16_f32 v87, v129, v130
	v_cvt_pk_bf16_f32 v86, v127, v128
	v_cvt_pk_bf16_f32 v85, v125, v126
	v_cvt_pk_bf16_f32 v84, v123, v124
	s_waitcnt lgkmcnt(6)
	s_nop 0
	v_mfma_f32_32x32x16_bf16 v[52:67], v[88:91], v[84:87], v[52:67]
	s_waitcnt lgkmcnt(4)
	v_mfma_f32_32x32x16_bf16 v[36:51], v[92:95], v[84:87], v[36:51]
	s_waitcnt lgkmcnt(2)
	v_mfma_f32_32x32x16_bf16 v[20:35], v[96:99], v[84:87], v[20:35]
	s_waitcnt lgkmcnt(0)
	v_mfma_f32_32x32x16_bf16 v[4:19], v[100:103], v[84:87], v[4:19]
	v_mfma_f32_32x32x16_bf16 v[68:83], v[116:119], v[84:87], v[68:83]
.LBB0_588:
	s_or_b64 exec, exec, s[0:1]
	s_setprio 0
	s_nop 10
	v_mov_b32_e32 v0, v68
	s_nop 1
	v_permlane32_swap_b32_e32 v68, v0
	v_add_f32_e32 v0, v68, v0
	v_div_scale_f32 v2, s[0:1], v0, v0, 1.0
	v_rcp_f32_e32 v3, v2
	s_barrier
	v_fma_f32 v68, -v2, v3, 1.0
	v_fmac_f32_e32 v3, v68, v3
	v_div_scale_f32 v68, vcc, 1.0, v0, 1.0
	v_mul_f32_e32 v69, v68, v3
	v_fma_f32 v70, -v2, v69, v68
	v_fmac_f32_e32 v69, v70, v3
	v_fma_f32 v2, -v2, v69, v68
	v_div_fmas_f32 v2, v2, v3, v69
	v_div_fixup_f32 v0, v2, v0, 1.0
	v_mul_u32_u24_e32 v2, 0x210, v167
	v_mul_u32_u24_e32 v3, 0x210, v163
	v_cmp_eq_u32_e32 vcc, 1, v166
	v_add3_u32 v72, v2, v3, v158
	s_and_saveexec_b64 s[0:1], vcc
	s_cbranch_execz .LBB0_590
	v_pk_mul_f32 v[68:69], v[52:53], v[0:1] op_sel_hi:[1,0]
	v_pk_mul_f32 v[70:71], v[54:55], v[0:1] op_sel_hi:[1,0]
	ds_write_b128 v72, v[68:71]
	v_pk_mul_f32 v[68:69], v[56:57], v[0:1] op_sel_hi:[1,0]
	v_pk_mul_f32 v[70:71], v[58:59], v[0:1] op_sel_hi:[1,0]
	ds_write_b128 v72, v[68:71] offset:32
	v_pk_mul_f32 v[68:69], v[60:61], v[0:1] op_sel_hi:[1,0]
	v_pk_mul_f32 v[70:71], v[62:63], v[0:1] op_sel_hi:[1,0]
	ds_write_b128 v72, v[68:71] offset:64
	v_pk_mul_f32 v[68:69], v[64:65], v[0:1] op_sel_hi:[1,0]
	v_pk_mul_f32 v[70:71], v[66:67], v[0:1] op_sel_hi:[1,0]
	ds_write_b128 v72, v[68:71] offset:96
	v_pk_mul_f32 v[68:69], v[36:37], v[0:1] op_sel_hi:[1,0]
	v_pk_mul_f32 v[70:71], v[38:39], v[0:1] op_sel_hi:[1,0]
	ds_write_b128 v72, v[68:71] offset:128
	v_pk_mul_f32 v[68:69], v[40:41], v[0:1] op_sel_hi:[1,0]
	v_pk_mul_f32 v[70:71], v[42:43], v[0:1] op_sel_hi:[1,0]
	ds_write_b128 v72, v[68:71] offset:160
	v_pk_mul_f32 v[68:69], v[44:45], v[0:1] op_sel_hi:[1,0]
	v_pk_mul_f32 v[70:71], v[46:47], v[0:1] op_sel_hi:[1,0]
	ds_write_b128 v72, v[68:71] offset:192
	v_pk_mul_f32 v[68:69], v[48:49], v[0:1] op_sel_hi:[1,0]
	v_pk_mul_f32 v[70:71], v[50:51], v[0:1] op_sel_hi:[1,0]
	ds_write_b128 v72, v[68:71] offset:224
	v_pk_mul_f32 v[68:69], v[20:21], v[0:1] op_sel_hi:[1,0]
	v_pk_mul_f32 v[70:71], v[22:23], v[0:1] op_sel_hi:[1,0]
	ds_write_b128 v72, v[68:71] offset:256
	v_pk_mul_f32 v[68:69], v[24:25], v[0:1] op_sel_hi:[1,0]
	v_pk_mul_f32 v[70:71], v[26:27], v[0:1] op_sel_hi:[1,0]
	ds_write_b128 v72, v[68:71] offset:288
	v_pk_mul_f32 v[68:69], v[28:29], v[0:1] op_sel_hi:[1,0]
	v_pk_mul_f32 v[70:71], v[30:31], v[0:1] op_sel_hi:[1,0]
	ds_write_b128 v72, v[68:71] offset:320
	v_pk_mul_f32 v[68:69], v[32:33], v[0:1] op_sel_hi:[1,0]
	v_pk_mul_f32 v[70:71], v[34:35], v[0:1] op_sel_hi:[1,0]
	ds_write_b128 v72, v[68:71] offset:352
	v_pk_mul_f32 v[68:69], v[4:5], v[0:1] op_sel_hi:[1,0]
	v_pk_mul_f32 v[70:71], v[6:7], v[0:1] op_sel_hi:[1,0]
	ds_write_b128 v72, v[68:71] offset:384
	v_pk_mul_f32 v[68:69], v[8:9], v[0:1] op_sel_hi:[1,0]
	v_pk_mul_f32 v[70:71], v[10:11], v[0:1] op_sel_hi:[1,0]
	ds_write_b128 v72, v[68:71] offset:416
	v_pk_mul_f32 v[68:69], v[12:13], v[0:1] op_sel_hi:[1,0]
	v_pk_mul_f32 v[70:71], v[14:15], v[0:1] op_sel_hi:[1,0]
	ds_write_b128 v72, v[68:71] offset:448
	v_pk_mul_f32 v[68:69], v[16:17], v[0:1] op_sel_hi:[1,0]
	v_pk_mul_f32 v[70:71], v[18:19], v[0:1] op_sel_hi:[1,0]
	ds_write_b128 v72, v[68:71] offset:480

; __global__ void __launch_bounds__(512, 1) mega_kernel(Params p, int ph_begin, int ph_end) {
;   __shared__ __attribute__((aligned(16))) char smem[SMEM_BYTES];
	.amdhsa_kernel _Z11mega_kernel6Paramsii
		.amdhsa_group_segment_fixed_size 154124
		.amdhsa_private_segment_fixed_size 0
		.amdhsa_kernarg_size 496
		.amdhsa_user_sgpr_count 2
		.amdhsa_user_sgpr_dispatch_ptr 0
		.amdhsa_user_sgpr_queue_ptr 0
		.amdhsa_user_sgpr_kernarg_segment_ptr 1
		.amdhsa_user_sgpr_dispatch_id 0
		.amdhsa_user_sgpr_kernarg_preload_length 0
		.amdhsa_user_sgpr_kernarg_preload_offset 0
		.amdhsa_user_sgpr_private_segment_size 0
		.amdhsa_uses_dynamic_stack 0
		.amdhsa_enable_private_segment 0
		.amdhsa_system_sgpr_workgroup_id_x 1
		.amdhsa_system_sgpr_workgroup_id_y 0
		.amdhsa_system_sgpr_workgroup_id_z 0
		.amdhsa_system_sgpr_workgroup_info 0
		.amdhsa_system_vgpr_workitem_id 2
		.amdhsa_next_free_vgpr 254
		.amdhsa_next_free_sgpr 99
		.amdhsa_accum_offset 256
		.amdhsa_reserve_vcc 1
		.amdhsa_float_round_mode_32 0
		.amdhsa_float_round_mode_16_64 0
		.amdhsa_float_denorm_mode_32 3
		.amdhsa_float_denorm_mode_16_64 3
		.amdhsa_dx10_clamp 1
		.amdhsa_ieee_mode 1
		.amdhsa_fp16_overflow 0
		.amdhsa_tg_split 0
		.amdhsa_exception_fp_ieee_invalid_op 0
		.amdhsa_exception_fp_denorm_src 0
		.amdhsa_exception_fp_ieee_div_zero 0
		.amdhsa_exception_fp_ieee_overflow 0
		.amdhsa_exception_fp_ieee_underflow 0
		.amdhsa_exception_fp_ieee_inexact 0
		.amdhsa_exception_int_div_zero 0
	.end_amdhsa_kernel

; __global__ void __launch_bounds__(512, 1) mega_kernel(Params p, int ph_begin, int ph_end) {
;   __shared__ __attribute__((aligned(16))) char smem[SMEM_BYTES];
amdhsa.kernels:
  - .agpr_count:     0
    .args:
      - .offset:         0
        .size:           232
        .value_kind:     by_value
      - .offset:         232
        .size:           4
        .value_kind:     by_value
      - .offset:         236
        .size:           4
        .value_kind:     by_value
      - .offset:         240
        .size:           4
        .value_kind:     hidden_block_count_x
      - .offset:         244
        .size:           4
        .value_kind:     hidden_block_count_y
      - .offset:         248
        .size:           4
        .value_kind:     hidden_block_count_z
      - .offset:         252
        .size:           2
        .value_kind:     hidden_group_size_x
      - .offset:         254
        .size:           2
        .value_kind:     hidden_group_size_y
      - .offset:         256
        .size:           2
        .value_kind:     hidden_group_size_z
      - .offset:         258
        .size:           2
        .value_kind:     hidden_remainder_x
      - .offset:         260
        .size:           2
        .value_kind:     hidden_remainder_y
      - .offset:         262
        .size:           2
        .value_kind:     hidden_remainder_z
      - .offset:         280
        .size:           8
        .value_kind:     hidden_global_offset_x
      - .offset:         288
        .size:           8
        .value_kind:     hidden_global_offset_y
      - .offset:         296
        .size:           8
        .value_kind:     hidden_global_offset_z
      - .offset:         304
        .size:           2
        .value_kind:     hidden_grid_dims
      - .offset:         328
        .size:           8
        .value_kind:     hidden_multigrid_sync_arg
    .group_segment_fixed_size: 154124
    .kernarg_segment_align: 8
    .kernarg_segment_size: 496
    .language:       OpenCL C
    .language_version:
      - 2
      - 0
    .max_flat_workgroup_size: 512
    .name:           _Z11mega_kernel6Paramsii
    .private_segment_fixed_size: 0
    .sgpr_count:     105
    .sgpr_spill_count: 98
    .symbol:         _Z11mega_kernel6Paramsii.kd
    .uniform_work_group_size: 1
    .uses_dynamic_stack: false
    .vgpr_count:     254
    .vgpr_spill_count: 0
    .wavefront_size: 64
